# adds: MLA K tile LDS swizzle over 16 rows (was 8) to remove 2-way bank conflicts in QK ds_read_b128
# speedup vs baseline: 1.0223x; 1.0006x over previous
.LBB0_138:
	s_andn2_b64 vcc, exec, s[18:19]
	s_cbranch_vccnz .LBB0_483
	s_cmp_lg_u32 s71, 6
	s_cselect_b64 s[56:57], -1, 0
	s_mov_b64 s[18:19], -1
	s_and_b64 vcc, exec, s[56:57]
	s_cbranch_vccz .LBB0_293
	v_writelane_b32 v255, s56, 7
	s_movk_i32 s8, 0x80
	s_movk_i32 s2, 0x88
	v_writelane_b32 v255, s57, 8
	v_writelane_b32 v255, s26, 10
	v_writelane_b32 v255, s55, 11
	v_writelane_b32 v255, s80, 9
	v_writelane_b32 v255, s31, 4
	s_cmpk_gt_i32 s99, 0x2ff
	s_cbranch_scc1 .LBB0_385
	s_ashr_i32 s9, s8, 31
	s_add_u32 s8, s0, s8
	s_addc_u32 s9, s1, s9
	s_ashr_i32 s19, s2, 31
	s_add_u32 s18, s0, s2
	s_addc_u32 s19, s1, s19
	v_ashrrev_i32_e32 v9, 4, v215
	s_load_dwordx2 s[8:9], s[8:9], 0x0
	s_nop 0
	s_load_dwordx2 s[18:19], s[18:19], 0x0
	s_waitcnt vmcnt(0)
	v_and_b32_e32 v4, 0xfffff0, v9
	v_lshlrev_b32_e32 v6, 1, v9
	s_add_i32 s2, s44, -2
	v_lshlrev_b32_e32 v5, 3, v215
	v_and_or_b32 v4, v6, 8, v4
	s_lshl_b32 s20, s2, 6
	v_and_b32_e32 v2, 0x78, v5
	v_lshrrev_b32_e32 v6, 1, v9
	v_lshrrev_b32_e32 v4, 1, v4
	v_bfe_u32 v10, v5, 5, 2
	v_and_b32_e32 v11, 3, v9
	s_ashr_i32 s21, s20, 31
	v_or_b32_e32 v4, v4, v10
	v_and_or_b32 v6, v6, 4, v11
	v_lshlrev_b32_e32 v11, 1, v2
	s_lshl_b64 s[20:21], s[20:21], 2
	v_lshlrev_b32_e32 v4, 9, v4
	v_lshlrev_b32_e32 v6, 6, v6
	v_and_b32_e32 v12, 48, v11
	v_add_u32_e32 v13, 32, v9
	s_waitcnt lgkmcnt(0)
	s_add_u32 s18, s18, s20
	v_or3_b32 v216, v4, v6, v12
	v_and_b32_e32 v4, 0xfffff0, v13
	v_lshlrev_b32_e32 v14, 1, v13
	s_addc_u32 s19, s19, s21
	s_lshl_b32 s20, s2, 7
	v_and_or_b32 v4, v14, 8, v4
	s_ashr_i32 s21, s20, 31
	v_lshrrev_b32_e32 v4, 1, v4
	s_lshl_b64 s[20:21], s[20:21], 2
	v_and_b32_e32 v168, 31, v166
	v_readlane_b32 s2, v255, 4
	v_or_b32_e32 v4, v4, v10
	s_add_u32 s8, s8, s20
	v_lshl_or_b32 v167, s2, 5, v168
	s_movk_i32 s2, 0xa00
	v_lshlrev_b32_e32 v4, 9, v4
	s_addc_u32 s9, s9, s21
	v_mad_i64_i32 v[170:171], s[20:21], v167, s2, 0
	v_or3_b32 v217, v4, v6, v12
	v_and_b32_e32 v6, 56, v5
	v_and_b32_e32 v7, 63, v166
	s_movk_i32 s20, 0x70
	v_lshlrev_b32_e32 v5, 1, v6
	v_lshlrev_b32_e32 v15, 4, v166
	v_bitop3_b32 v14, v5, v215, s20 bitop3:0x78
	v_lshlrev_b32_e32 v5, 3, v7
	v_and_b32_e32 v16, 0xc0, v15
	v_lshlrev_b32_e32 v17, 1, v166
	v_ashrrev_i32_e32 v3, 2, v166
	v_and_or_b32 v16, v5, 24, v16
	v_and_b32_e32 v17, 32, v17
	v_and_b32_e32 v5, 0x100, v5
	s_cmp_lg_u32 0, -1
	v_and_b32_e32 v172, -8, v3
	v_ashrrev_i32_e32 v4, 3, v215
	v_or3_b32 v5, v16, v17, v5
	s_cselect_b32 s2, 0, 0
	v_ashrrev_i32_e32 v173, 31, v172
	v_add_u32_e32 v218, s2, v5
	v_ashrrev_i32_e32 v5, 31, v4
	v_lshlrev_b64 v[0:1], 2, v[172:173]
	v_lshlrev_b32_e32 v12, 7, v4
	s_movk_i32 s21, 0x600
	v_lshlrev_b64 v[180:181], 7, v[4:5]
	v_add_u32_e32 v4, 64, v9
	v_lshl_add_u64 v[174:175], s[8:9], 0, v[0:1]
	v_mad_i64_i32 v[182:183], s[8:9], v4, s21, 0
	v_add_u32_e32 v4, 0x60, v9
	v_mad_i64_i32 v[176:177], s[8:9], v9, s21, 0
	v_mad_i64_i32 v[178:179], s[8:9], v13, s21, 0
	s_add_i32 s2, 0, 0x14000
	v_mad_i64_i32 v[184:185], s[8:9], v4, s21, 0
	v_bfe_u32 v8, v166, 5, 1
	s_getpc_b64 s[8:9]
	s_add_u32 s8, s8, INVF@rel32@lo+4
	s_addc_u32 s9, s9, INVF@rel32@hi+12
	v_add3_u32 v220, s2, v14, v12
	v_lshlrev_b32_e32 v4, 4, v8
	v_and_b32_e32 v5, 0x70, v15
	s_movk_i32 s2, 0x60
	v_lshl_add_u64 v[190:191], s[18:19], 0, v[0:1]
	v_lshl_add_u64 v[192:193], s[8:9], 0, v[0:1]
	v_or_b32_e32 v0, 7, v3
	v_lshlrev_b32_e32 v10, 8, v9
	v_bitop3_b32 v11, v11, v215, s20 bitop3:0x78
	v_bitop3_b32 v223, v4, v5, 32 bitop3:0x36
	v_bitop3_b32 v224, v4, v5, 64 bitop3:0x36
	v_bitop3_b32 v225, v4, v5, s2 bitop3:0x36
	v_lshlrev_b32_e32 v5, 3, v166
	v_ashrrev_i32_e32 v1, 31, v0
	v_add3_u32 v219, 0, v11, v10
	v_and_b32_e32 v10, 0x70, v5
	v_lshlrev_b64 v[0:1], 2, v[0:1]
	v_bitop3_b32 v230, v4, v10, s2 bitop3:0x36
	v_lshl_add_u64 v[194:195], s[18:19], 0, v[0:1]
	v_lshl_add_u64 v[196:197], s[8:9], 0, v[0:1]
	v_and_b32_e32 v0, 7, v215
	s_movk_i32 s2, 0xc00
	v_bitop3_b32 v222, v4, v15, s20 bitop3:0x78
	v_bitop3_b32 v227, v4, v5, s20 bitop3:0x78
	v_bitop3_b32 v228, v4, v10, 32 bitop3:0x36
	v_bitop3_b32 v229, v4, v10, 64 bitop3:0x36
	v_and_b32_e32 v4, 1, v166
	v_lshl_or_b32 v198, v0, 4, v180
	v_mad_i64_i32 v[200:201], s[8:9], v9, s2, 0
	v_lshlrev_b32_e32 v0, 4, v215
	s_movk_i32 s2, 0xf0
	v_lshlrev_b32_e32 v169, 2, v8
	v_lshl_add_u64 v[186:187], v[180:181], 0, s[96:97]
	v_lshlrev_b32_e32 v221, 8, v168
	v_and_b32_e32 v232, 0x80, v215
	v_xor_b32_e32 v219, v219, v232
	v_and_b32_e32 v232, 8, v166
	v_lshlrev_b32_e32 v232, 4, v232
	v_or_b32_e32 v222, v222, v232
	v_or_b32_e32 v223, v223, v232
	v_or_b32_e32 v224, v224, v232
	v_or_b32_e32 v225, v225, v232
	v_lshlrev_b32_e32 v226, 7, v168
	v_cmp_gt_u32_e64 s[38:39], 32, v7
	v_cmp_eq_u32_e64 s[40:41], 0, v4
	v_lshlrev_b32_e32 v188, 13, v8
	v_mov_b32_e32 v189, v97
	v_mov_b32_e32 v199, v181
	v_and_or_b32 v200, v0, s2, v200
	v_lshlrev_b32_e32 v202, 1, v2
	v_lshlrev_b32_e32 v204, 1, v6
	v_lshlrev_b32_e32 v96, 1, v168
	s_mov_b32 s45, s99
	s_branch .LBB0_143

.LBB0_148:
	s_add_i32 s36, s57, -2
	s_and_b32 s74, s36, 1
	s_lshl_b32 s36, s74, 14
	s_lshl_b32 s42, s74, 13
	s_add_i32 s42, s42, 0x14000
	v_add3_u32 v210, s36, v222, v221
	v_add3_u32 v211, s36, v223, v221
	v_add3_u32 v212, s36, v224, v221
	v_add3_u32 v213, s36, v225, v221
	ds_read_b128 v[240:243], v210 offset:49152
	ds_read_b128 v[244:247], v211 offset:49152
	ds_read_b128 v[248:251], v212 offset:49152
	ds_read_b128 v[236:239], v213 offset:49152
	v_xor_b32_e32 v210, 0x80, v210
	v_xor_b32_e32 v211, 0x80, v211
	v_xor_b32_e32 v212, 0x80, v212
	v_xor_b32_e32 v213, 0x80, v213
	ds_read_b128 v[64:67], v210 offset:49152
	ds_read_b128 v[68:71], v211 offset:49152
	ds_read_b128 v[72:75], v212 offset:49152
	ds_read_b128 v[76:79], v213 offset:49152
	v_xor_b32_e32 v210, 0x80, v210
	v_xor_b32_e32 v211, 0x80, v211
	v_xor_b32_e32 v212, 0x80, v212
	v_xor_b32_e32 v213, 0x80, v213
	v_add3_u32 v234, s42, v227, v226
	v_add3_u32 v235, s42, v228, v226
	s_waitcnt lgkmcnt(7)
	v_mfma_f32_32x32x16_bf16 v[80:95], v[240:243], v[98:101], 0
	ds_read_b128 v[240:243], v234
	s_waitcnt lgkmcnt(7)
	v_mfma_f32_32x32x16_bf16 v[80:95], v[244:247], v[102:105], v[80:95]
	ds_read_b128 v[244:247], v235
	v_add3_u32 v234, s42, v229, v226
	v_add3_u32 v235, s42, v230, v226
	s_waitcnt lgkmcnt(7)
	v_mfma_f32_32x32x16_bf16 v[80:95], v[248:251], v[106:109], v[80:95]
	ds_read_b128 v[248:251], v234
	s_waitcnt lgkmcnt(7)
	v_mfma_f32_32x32x16_bf16 v[80:95], v[236:239], v[110:113], v[80:95]
	ds_read_b128 v[236:239], v235
	s_waitcnt lgkmcnt(7)
	v_mfma_f32_32x32x16_bf16 v[80:95], v[64:67], v[114:117], v[80:95]
	ds_read_b128 v[64:67], v210 offset:57344
	v_xor_b32_e32 v210, 0x80, v210
	s_waitcnt lgkmcnt(7)
	v_mfma_f32_32x32x16_bf16 v[80:95], v[68:71], v[118:121], v[80:95]
	s_waitcnt lgkmcnt(6)
	v_mfma_f32_32x32x16_bf16 v[80:95], v[72:75], v[122:125], v[80:95]
	s_waitcnt lgkmcnt(5)
	v_mfma_f32_32x32x16_bf16 v[80:95], v[76:79], v[126:129], v[80:95]
	s_waitcnt lgkmcnt(4)
	v_mfma_f32_32x32x16_bf16 v[80:95], v[240:243], v[130:133], v[80:95]
	ds_read_b128 v[240:243], v211 offset:57344
	v_xor_b32_e32 v211, 0x80, v211
	s_waitcnt lgkmcnt(4)
	v_mfma_f32_32x32x16_bf16 v[80:95], v[244:247], v[138:141], v[80:95]
	ds_read_b128 v[244:247], v212 offset:57344
	v_xor_b32_e32 v212, 0x80, v212
	s_waitcnt lgkmcnt(4)
	v_mfma_f32_32x32x16_bf16 v[80:95], v[248:251], v[134:137], v[80:95]
	ds_read_b128 v[248:251], v213 offset:57344
	v_xor_b32_e32 v213, 0x80, v213
	s_waitcnt lgkmcnt(4)
	v_mfma_f32_32x32x16_bf16 v[80:95], v[236:239], v[142:145], v[80:95]
	ds_read_b128 v[236:239], v210 offset:57344
	s_waitcnt lgkmcnt(4)
	v_mfma_f32_32x32x16_bf16 v[64:79], v[64:67], v[98:101], 0
	s_waitcnt lgkmcnt(3)
	v_mfma_f32_32x32x16_bf16 v[64:79], v[240:243], v[102:105], v[64:79]
	ds_read_b128 v[240:243], v211 offset:57344
	s_waitcnt lgkmcnt(3)
	v_mfma_f32_32x32x16_bf16 v[64:79], v[244:247], v[106:109], v[64:79]
	ds_read_b128 v[244:247], v212 offset:57344
	v_add3_u32 v210, s42, v227, v226
	s_waitcnt lgkmcnt(3)
	v_mfma_f32_32x32x16_bf16 v[64:79], v[248:251], v[110:113], v[64:79]
	ds_read_b128 v[248:251], v213 offset:57344
	v_add3_u32 v211, s42, v228, v226
	s_waitcnt lgkmcnt(3)
	v_mfma_f32_32x32x16_bf16 v[64:79], v[236:239], v[114:117], v[64:79]
	ds_read_b128 v[236:239], v210 offset:4096
	v_add3_u32 v212, s42, v229, v226
	s_waitcnt lgkmcnt(3)
	v_mfma_f32_32x32x16_bf16 v[64:79], v[240:243], v[118:121], v[64:79]
	ds_read_b128 v[240:243], v211 offset:4096
	v_add3_u32 v213, s42, v230, v226
	s_waitcnt lgkmcnt(3)
	v_mfma_f32_32x32x16_bf16 v[64:79], v[244:247], v[122:125], v[64:79]
	ds_read_b128 v[244:247], v212 offset:4096
	s_waitcnt lgkmcnt(3)
	v_mfma_f32_32x32x16_bf16 v[64:79], v[248:251], v[126:129], v[64:79]
	ds_read_b128 v[248:251], v213 offset:4096
	s_waitcnt lgkmcnt(3)
	v_mfma_f32_32x32x16_bf16 v[64:79], v[236:239], v[130:133], v[64:79]
	s_waitcnt lgkmcnt(2)
	v_mfma_f32_32x32x16_bf16 v[64:79], v[240:243], v[138:141], v[64:79]
	s_waitcnt lgkmcnt(1)
	v_mfma_f32_32x32x16_bf16 v[64:79], v[244:247], v[134:137], v[64:79]
	s_waitcnt lgkmcnt(0)
	v_mfma_f32_32x32x16_bf16 v[64:79], v[248:251], v[142:145], v[64:79]
	s_add_i32 s36, s8, 63
	s_cmp_le_i32 s36, s2
	s_cselect_b64 s[36:37], -1, 0
	s_cmp_gt_i32 s8, s55
	s_cselect_b64 s[42:43], -1, 0
	s_and_b64 s[36:37], s[36:37], s[42:43]
	s_and_b64 vcc, exec, s[36:37]
	s_cbranch_vccnz .LBB0_150
	v_add_u32_e32 v210, s69, v231
	v_cmp_gt_u32_e32 vcc, s66, v210
	v_add_u32_e32 v211, 0xffefffe0, v210
	s_nop 0
	v_cndmask_b32_e32 v80, v214, v80, vcc
	v_cmp_lt_u32_e32 vcc, s67, v211
	v_add_u32_e32 v211, 0xffefffff, v210
	s_nop 0
	v_cndmask_b32_e32 v64, v214, v64, vcc
	v_cmp_lt_u32_e32 vcc, s67, v211
	v_add_u32_e32 v211, 0xffefffdf, v210
	s_nop 0
	v_cndmask_b32_e32 v81, v214, v81, vcc
	v_cmp_lt_u32_e32 vcc, s67, v211
	v_add_u32_e32 v211, 0xffeffffe, v210
	s_nop 0
	v_cndmask_b32_e32 v65, v214, v65, vcc
	v_cmp_lt_u32_e32 vcc, s67, v211
	v_add_u32_e32 v211, 0xffefffde, v210
	s_nop 0
	v_cndmask_b32_e32 v82, v214, v82, vcc
	v_cmp_lt_u32_e32 vcc, s67, v211
	v_add_u32_e32 v211, 0xffeffffd, v210
	s_nop 0
	v_cndmask_b32_e32 v66, v214, v66, vcc
	v_cmp_lt_u32_e32 vcc, s67, v211
	v_add_u32_e32 v211, 0xffefffdd, v210
	s_nop 0
	v_cndmask_b32_e32 v83, v214, v83, vcc
	v_cmp_lt_u32_e32 vcc, s67, v211
	v_add_u32_e32 v211, 0xffeffff8, v210
	s_nop 0
	v_cndmask_b32_e32 v67, v214, v67, vcc
	v_cmp_lt_u32_e32 vcc, s67, v211
	v_add_u32_e32 v211, 0xffefffd8, v210
	s_nop 0
	v_cndmask_b32_e32 v84, v214, v84, vcc
	v_cmp_lt_u32_e32 vcc, s67, v211
	v_add_u32_e32 v211, 0xffeffff7, v210
	s_nop 0
	v_cndmask_b32_e32 v68, v214, v68, vcc
	v_cmp_lt_u32_e32 vcc, s67, v211
	v_add_u32_e32 v211, 0xffefffd7, v210
	s_nop 0
	v_cndmask_b32_e32 v85, v214, v85, vcc
	v_cmp_lt_u32_e32 vcc, s67, v211
	v_add_u32_e32 v211, 0xffeffff6, v210
	s_nop 0
	v_cndmask_b32_e32 v69, v214, v69, vcc
	v_cmp_lt_u32_e32 vcc, s67, v211
	v_add_u32_e32 v211, 0xffefffd6, v210
	s_nop 0
	v_cndmask_b32_e32 v86, v214, v86, vcc
	v_cmp_lt_u32_e32 vcc, s67, v211
	v_add_u32_e32 v211, 0xffeffff5, v210
	s_nop 0
	v_cndmask_b32_e32 v70, v214, v70, vcc
	v_cmp_lt_u32_e32 vcc, s67, v211
	v_add_u32_e32 v211, 0xffefffd5, v210
	s_nop 0
	v_cndmask_b32_e32 v87, v214, v87, vcc
	v_cmp_lt_u32_e32 vcc, s67, v211
	v_add_u32_e32 v211, 0xffeffff0, v210
	s_nop 0
	v_cndmask_b32_e32 v71, v214, v71, vcc
	v_cmp_lt_u32_e32 vcc, s67, v211
	v_add_u32_e32 v211, 0xffefffd0, v210
	s_nop 0
	v_cndmask_b32_e32 v88, v214, v88, vcc
	v_cmp_lt_u32_e32 vcc, s67, v211
	v_add_u32_e32 v211, 0xffefffef, v210
	s_nop 0
	v_cndmask_b32_e32 v72, v214, v72, vcc
	v_cmp_lt_u32_e32 vcc, s67, v211
	v_add_u32_e32 v211, 0xffefffcf, v210
	s_nop 0
	v_cndmask_b32_e32 v89, v214, v89, vcc
	v_cmp_lt_u32_e32 vcc, s67, v211
	v_add_u32_e32 v211, 0xffefffee, v210
	s_nop 0
	v_cndmask_b32_e32 v73, v214, v73, vcc
	v_cmp_lt_u32_e32 vcc, s67, v211
	v_add_u32_e32 v211, 0xffefffce, v210
	s_nop 0
	v_cndmask_b32_e32 v90, v214, v90, vcc
	v_cmp_lt_u32_e32 vcc, s67, v211
	v_add_u32_e32 v211, 0xffefffed, v210
	s_nop 0
	v_cndmask_b32_e32 v74, v214, v74, vcc
	v_cmp_lt_u32_e32 vcc, s67, v211
	v_add_u32_e32 v211, 0xffefffcd, v210
	s_nop 0
	v_cndmask_b32_e32 v91, v214, v91, vcc
	v_cmp_lt_u32_e32 vcc, s67, v211
	v_add_u32_e32 v211, 0xffefffe8, v210
	s_nop 0
	v_cndmask_b32_e32 v75, v214, v75, vcc
	v_cmp_lt_u32_e32 vcc, s67, v211
	v_add_u32_e32 v211, 0xffefffc8, v210
	s_nop 0
	v_cndmask_b32_e32 v92, v214, v92, vcc
	v_cmp_lt_u32_e32 vcc, s67, v211
	v_add_u32_e32 v211, 0xffefffe7, v210
	s_nop 0
	v_cndmask_b32_e32 v76, v214, v76, vcc
	v_cmp_lt_u32_e32 vcc, s67, v211
	v_add_u32_e32 v211, 0xffefffc7, v210
	s_nop 0
	v_cndmask_b32_e32 v93, v214, v93, vcc
	v_cmp_lt_u32_e32 vcc, s67, v211
	v_add_u32_e32 v211, 0xffefffe6, v210
	s_nop 0
	v_cndmask_b32_e32 v77, v214, v77, vcc
	v_cmp_lt_u32_e32 vcc, s67, v211
	v_add_u32_e32 v211, 0xffefffc6, v210
	s_nop 0
	v_cndmask_b32_e32 v94, v214, v94, vcc
	v_cmp_lt_u32_e32 vcc, s67, v211
	v_add_u32_e32 v211, 0xffefffe5, v210
	v_add_u32_e32 v210, 0xffefffc5, v210
	v_cndmask_b32_e32 v78, v214, v78, vcc
	v_cmp_lt_u32_e32 vcc, s67, v211
	s_nop 1
	v_cndmask_b32_e32 v95, v214, v95, vcc
	v_cmp_lt_u32_e32 vcc, s67, v210
	s_nop 1
	v_cndmask_b32_e32 v79, v214, v79, vcc
